# gate_up epilogue (SwiGLU): scalar f32 multiplies/adds replaced by packed f32 ops on accumulator pairs, packed into dead gate quads per store group
# baseline (speedup 1.0000x reference)
.LBB0_801:
	v_mov_b32_e32 v204, 0xbfb8aa3b
	v_pk_mul_f32 v[200:201], v[116:117], v[204:205] op_sel_hi:[1,0]
	v_pk_mul_f32 v[202:203], v[118:119], v[204:205] op_sel_hi:[1,0]
	v_pk_mul_f32 v[112:113], v[116:117], v[112:113]
	v_pk_mul_f32 v[114:115], v[118:119], v[114:115]
	v_exp_f32_e32 v200, v200
	v_exp_f32_e32 v201, v201
	v_exp_f32_e32 v202, v202
	v_exp_f32_e32 v203, v203
	s_nop 0
	v_pk_add_f32 v[200:201], v[200:201], 1.0 op_sel_hi:[1,0]
	v_pk_add_f32 v[202:203], v[202:203], 1.0 op_sel_hi:[1,0]
	v_rcp_f32_e32 v200, v200
	v_rcp_f32_e32 v201, v201
	v_rcp_f32_e32 v202, v202
	v_rcp_f32_e32 v203, v203
	s_nop 0
	v_pk_mul_f32 v[112:113], v[200:201], v[112:113]
	v_pk_mul_f32 v[114:115], v[202:203], v[114:115]
	v_pk_mul_f32 v[206:207], v[124:125], v[204:205] op_sel_hi:[1,0]
	v_pk_mul_f32 v[208:209], v[126:127], v[204:205] op_sel_hi:[1,0]
	v_pk_mul_f32 v[120:121], v[124:125], v[120:121]
	v_pk_mul_f32 v[122:123], v[126:127], v[122:123]
	v_exp_f32_e32 v206, v206
	v_exp_f32_e32 v207, v207
	v_exp_f32_e32 v208, v208
	v_exp_f32_e32 v209, v209
	s_nop 0
	v_pk_add_f32 v[206:207], v[206:207], 1.0 op_sel_hi:[1,0]
	v_pk_add_f32 v[208:209], v[208:209], 1.0 op_sel_hi:[1,0]
	v_rcp_f32_e32 v206, v206
	v_rcp_f32_e32 v207, v207
	v_rcp_f32_e32 v208, v208
	v_rcp_f32_e32 v209, v209
	s_nop 0
	v_pk_mul_f32 v[120:121], v[206:207], v[120:121]
	v_pk_mul_f32 v[122:123], v[208:209], v[122:123]
	v_cvt_pk_bf16_f32 v124, v120, v121
	v_cvt_pk_bf16_f32 v125, v122, v123
	v_cvt_pk_bf16_f32 v126, v112, v113
	v_cvt_pk_bf16_f32 v127, v114, v115
	v_lshl_or_b32 v158, s57, 7, v150
	v_lshl_add_u32 v156, s24, 8, v148
	v_ashrrev_i32_e32 v159, 31, v158
	v_mov_b64_e32 v[112:113], s[8:9]
	v_mad_i64_i32 v[120:121], s[26:27], v156, s56, v[112:113]
	v_lshlrev_b64 v[114:115], 1, v[158:159]
	v_lshl_add_u64 v[120:121], v[120:121], 0, v[114:115]
	global_store_dwordx4 v[120:121], v[124:127], off
	v_pk_mul_f32 v[200:201], v[100:101], v[204:205] op_sel_hi:[1,0]
	v_pk_mul_f32 v[202:203], v[102:103], v[204:205] op_sel_hi:[1,0]
	v_pk_mul_f32 v[96:97], v[100:101], v[96:97]
	v_pk_mul_f32 v[98:99], v[102:103], v[98:99]
	v_exp_f32_e32 v200, v200
	v_exp_f32_e32 v201, v201
	v_exp_f32_e32 v202, v202
	v_exp_f32_e32 v203, v203
	s_nop 0
	v_pk_add_f32 v[200:201], v[200:201], 1.0 op_sel_hi:[1,0]
	v_pk_add_f32 v[202:203], v[202:203], 1.0 op_sel_hi:[1,0]
	v_rcp_f32_e32 v200, v200
	v_rcp_f32_e32 v201, v201
	v_rcp_f32_e32 v202, v202
	v_rcp_f32_e32 v203, v203
	s_nop 0
	v_pk_mul_f32 v[96:97], v[200:201], v[96:97]
	v_pk_mul_f32 v[98:99], v[202:203], v[98:99]
	v_pk_mul_f32 v[206:207], v[108:109], v[204:205] op_sel_hi:[1,0]
	v_pk_mul_f32 v[208:209], v[110:111], v[204:205] op_sel_hi:[1,0]
	v_pk_mul_f32 v[104:105], v[108:109], v[104:105]
	v_pk_mul_f32 v[106:107], v[110:111], v[106:107]
	v_exp_f32_e32 v206, v206
	v_exp_f32_e32 v207, v207
	v_exp_f32_e32 v208, v208
	v_exp_f32_e32 v209, v209
	s_nop 0
	v_pk_add_f32 v[206:207], v[206:207], 1.0 op_sel_hi:[1,0]
	v_pk_add_f32 v[208:209], v[208:209], 1.0 op_sel_hi:[1,0]
	v_rcp_f32_e32 v206, v206
	v_rcp_f32_e32 v207, v207
	v_rcp_f32_e32 v208, v208
	v_rcp_f32_e32 v209, v209
	s_nop 0
	v_pk_mul_f32 v[104:105], v[206:207], v[104:105]
	v_pk_mul_f32 v[106:107], v[208:209], v[106:107]
	v_cvt_pk_bf16_f32 v108, v104, v105
	v_cvt_pk_bf16_f32 v109, v106, v107
	v_cvt_pk_bf16_f32 v110, v96, v97
	v_cvt_pk_bf16_f32 v111, v98, v99
	v_or_b32_e32 v100, 16, v156
	v_mad_i64_i32 v[100:101], s[26:27], v100, s56, v[112:113]
	v_lshl_add_u64 v[100:101], v[100:101], 0, v[114:115]
	global_store_dwordx4 v[100:101], v[108:111], off
	v_pk_mul_f32 v[200:201], v[84:85], v[204:205] op_sel_hi:[1,0]
	v_pk_mul_f32 v[202:203], v[86:87], v[204:205] op_sel_hi:[1,0]
	v_pk_mul_f32 v[80:81], v[84:85], v[80:81]
	v_pk_mul_f32 v[82:83], v[86:87], v[82:83]
	v_exp_f32_e32 v200, v200
	v_exp_f32_e32 v201, v201
	v_exp_f32_e32 v202, v202
	v_exp_f32_e32 v203, v203
	s_nop 0
	v_pk_add_f32 v[200:201], v[200:201], 1.0 op_sel_hi:[1,0]
	v_pk_add_f32 v[202:203], v[202:203], 1.0 op_sel_hi:[1,0]
	v_rcp_f32_e32 v200, v200
	v_rcp_f32_e32 v201, v201
	v_rcp_f32_e32 v202, v202
	v_rcp_f32_e32 v203, v203
	s_nop 0
	v_pk_mul_f32 v[80:81], v[200:201], v[80:81]
	v_pk_mul_f32 v[82:83], v[202:203], v[82:83]
	v_pk_mul_f32 v[206:207], v[92:93], v[204:205] op_sel_hi:[1,0]
	v_pk_mul_f32 v[208:209], v[94:95], v[204:205] op_sel_hi:[1,0]
	v_pk_mul_f32 v[88:89], v[92:93], v[88:89]
	v_pk_mul_f32 v[90:91], v[94:95], v[90:91]
	v_exp_f32_e32 v206, v206
	v_exp_f32_e32 v207, v207
	v_exp_f32_e32 v208, v208
	v_exp_f32_e32 v209, v209
	s_nop 0
	v_pk_add_f32 v[206:207], v[206:207], 1.0 op_sel_hi:[1,0]
	v_pk_add_f32 v[208:209], v[208:209], 1.0 op_sel_hi:[1,0]
	v_rcp_f32_e32 v206, v206
	v_rcp_f32_e32 v207, v207
	v_rcp_f32_e32 v208, v208
	v_rcp_f32_e32 v209, v209
	s_nop 0
	v_pk_mul_f32 v[88:89], v[206:207], v[88:89]
	v_pk_mul_f32 v[90:91], v[208:209], v[90:91]
	v_cvt_pk_bf16_f32 v92, v88, v89
	v_cvt_pk_bf16_f32 v93, v90, v91
	v_cvt_pk_bf16_f32 v94, v80, v81
	v_cvt_pk_bf16_f32 v95, v82, v83
	v_or_b32_e32 v84, 32, v156
	v_mad_i64_i32 v[84:85], s[26:27], v84, s56, v[112:113]
	v_lshl_add_u64 v[84:85], v[84:85], 0, v[114:115]
	global_store_dwordx4 v[84:85], v[92:95], off
	v_pk_mul_f32 v[200:201], v[68:69], v[204:205] op_sel_hi:[1,0]
	v_pk_mul_f32 v[202:203], v[70:71], v[204:205] op_sel_hi:[1,0]
	v_pk_mul_f32 v[64:65], v[68:69], v[64:65]
	v_pk_mul_f32 v[66:67], v[70:71], v[66:67]
	v_exp_f32_e32 v200, v200
	v_exp_f32_e32 v201, v201
	v_exp_f32_e32 v202, v202
	v_exp_f32_e32 v203, v203
	s_nop 0
	v_pk_add_f32 v[200:201], v[200:201], 1.0 op_sel_hi:[1,0]
	v_pk_add_f32 v[202:203], v[202:203], 1.0 op_sel_hi:[1,0]
	v_rcp_f32_e32 v200, v200
	v_rcp_f32_e32 v201, v201
	v_rcp_f32_e32 v202, v202
	v_rcp_f32_e32 v203, v203
	s_nop 0
	v_pk_mul_f32 v[64:65], v[200:201], v[64:65]
	v_pk_mul_f32 v[66:67], v[202:203], v[66:67]
	v_pk_mul_f32 v[206:207], v[76:77], v[204:205] op_sel_hi:[1,0]
	v_pk_mul_f32 v[208:209], v[78:79], v[204:205] op_sel_hi:[1,0]
	v_pk_mul_f32 v[72:73], v[76:77], v[72:73]
	v_pk_mul_f32 v[74:75], v[78:79], v[74:75]
	v_exp_f32_e32 v206, v206
	v_exp_f32_e32 v207, v207
	v_exp_f32_e32 v208, v208
	v_exp_f32_e32 v209, v209
	s_nop 0
	v_pk_add_f32 v[206:207], v[206:207], 1.0 op_sel_hi:[1,0]
	v_pk_add_f32 v[208:209], v[208:209], 1.0 op_sel_hi:[1,0]
	v_rcp_f32_e32 v206, v206
	v_rcp_f32_e32 v207, v207
	v_rcp_f32_e32 v208, v208
	v_rcp_f32_e32 v209, v209
	s_nop 0
	v_pk_mul_f32 v[72:73], v[206:207], v[72:73]
	v_pk_mul_f32 v[74:75], v[208:209], v[74:75]
	v_cvt_pk_bf16_f32 v76, v72, v73
	v_cvt_pk_bf16_f32 v77, v74, v75
	v_cvt_pk_bf16_f32 v78, v64, v65
	v_cvt_pk_bf16_f32 v79, v66, v67
	v_or_b32_e32 v68, 48, v156
	v_mad_i64_i32 v[68:69], s[26:27], v68, s56, v[112:113]
	v_lshl_add_u64 v[68:69], v[68:69], 0, v[114:115]
	global_store_dwordx4 v[68:69], v[76:79], off
	v_pk_mul_f32 v[200:201], v[52:53], v[204:205] op_sel_hi:[1,0]
	v_pk_mul_f32 v[202:203], v[54:55], v[204:205] op_sel_hi:[1,0]
	v_pk_mul_f32 v[48:49], v[52:53], v[48:49]
	v_pk_mul_f32 v[50:51], v[54:55], v[50:51]
	v_exp_f32_e32 v200, v200
	v_exp_f32_e32 v201, v201
	v_exp_f32_e32 v202, v202
	v_exp_f32_e32 v203, v203
	s_nop 0
	v_pk_add_f32 v[200:201], v[200:201], 1.0 op_sel_hi:[1,0]
	v_pk_add_f32 v[202:203], v[202:203], 1.0 op_sel_hi:[1,0]
	v_rcp_f32_e32 v200, v200
	v_rcp_f32_e32 v201, v201
	v_rcp_f32_e32 v202, v202
	v_rcp_f32_e32 v203, v203
	s_nop 0
	v_pk_mul_f32 v[48:49], v[200:201], v[48:49]
	v_pk_mul_f32 v[50:51], v[202:203], v[50:51]
	v_pk_mul_f32 v[206:207], v[60:61], v[204:205] op_sel_hi:[1,0]
	v_pk_mul_f32 v[208:209], v[62:63], v[204:205] op_sel_hi:[1,0]
	v_pk_mul_f32 v[56:57], v[60:61], v[56:57]
	v_pk_mul_f32 v[58:59], v[62:63], v[58:59]
	v_exp_f32_e32 v206, v206
	v_exp_f32_e32 v207, v207
	v_exp_f32_e32 v208, v208
	v_exp_f32_e32 v209, v209
	s_nop 0
	v_pk_add_f32 v[206:207], v[206:207], 1.0 op_sel_hi:[1,0]
	v_pk_add_f32 v[208:209], v[208:209], 1.0 op_sel_hi:[1,0]
	v_rcp_f32_e32 v206, v206
	v_rcp_f32_e32 v207, v207
	v_rcp_f32_e32 v208, v208
	v_rcp_f32_e32 v209, v209
	s_nop 0
	v_pk_mul_f32 v[56:57], v[206:207], v[56:57]
	v_pk_mul_f32 v[58:59], v[208:209], v[58:59]
	v_cvt_pk_bf16_f32 v60, v56, v57
	v_cvt_pk_bf16_f32 v61, v58, v59
	v_cvt_pk_bf16_f32 v62, v48, v49
	v_cvt_pk_bf16_f32 v63, v50, v51
	v_add_u32_e32 v66, 0x80, v156
	v_mad_i64_i32 v[52:53], s[26:27], v66, s56, v[112:113]
	v_lshl_add_u64 v[52:53], v[52:53], 0, v[114:115]
	global_store_dwordx4 v[52:53], v[60:63], off
	v_pk_mul_f32 v[200:201], v[36:37], v[204:205] op_sel_hi:[1,0]
	v_pk_mul_f32 v[202:203], v[38:39], v[204:205] op_sel_hi:[1,0]
	v_pk_mul_f32 v[32:33], v[36:37], v[32:33]
	v_pk_mul_f32 v[34:35], v[38:39], v[34:35]
	v_exp_f32_e32 v200, v200
	v_exp_f32_e32 v201, v201
	v_exp_f32_e32 v202, v202
	v_exp_f32_e32 v203, v203
	s_nop 0
	v_pk_add_f32 v[200:201], v[200:201], 1.0 op_sel_hi:[1,0]
	v_pk_add_f32 v[202:203], v[202:203], 1.0 op_sel_hi:[1,0]
	v_rcp_f32_e32 v200, v200
	v_rcp_f32_e32 v201, v201
	v_rcp_f32_e32 v202, v202
	v_rcp_f32_e32 v203, v203
	s_nop 0
	v_pk_mul_f32 v[32:33], v[200:201], v[32:33]
	v_pk_mul_f32 v[34:35], v[202:203], v[34:35]
	v_pk_mul_f32 v[206:207], v[44:45], v[204:205] op_sel_hi:[1,0]
	v_pk_mul_f32 v[208:209], v[46:47], v[204:205] op_sel_hi:[1,0]
	v_pk_mul_f32 v[40:41], v[44:45], v[40:41]
	v_pk_mul_f32 v[42:43], v[46:47], v[42:43]
	v_exp_f32_e32 v206, v206
	v_exp_f32_e32 v207, v207
	v_exp_f32_e32 v208, v208
	v_exp_f32_e32 v209, v209
	s_nop 0
	v_pk_add_f32 v[206:207], v[206:207], 1.0 op_sel_hi:[1,0]
	v_pk_add_f32 v[208:209], v[208:209], 1.0 op_sel_hi:[1,0]
	v_rcp_f32_e32 v206, v206
	v_rcp_f32_e32 v207, v207
	v_rcp_f32_e32 v208, v208
	v_rcp_f32_e32 v209, v209
	s_nop 0
	v_pk_mul_f32 v[40:41], v[206:207], v[40:41]
	v_pk_mul_f32 v[42:43], v[208:209], v[42:43]
	v_cvt_pk_bf16_f32 v44, v40, v41
	v_cvt_pk_bf16_f32 v45, v42, v43
	v_cvt_pk_bf16_f32 v46, v32, v33
	v_cvt_pk_bf16_f32 v47, v34, v35
	v_add_u32_e32 v36, 0x90, v156
	v_mad_i64_i32 v[36:37], s[26:27], v36, s56, v[112:113]
	v_lshl_add_u64 v[36:37], v[36:37], 0, v[114:115]
	global_store_dwordx4 v[36:37], v[44:47], off
	v_pk_mul_f32 v[200:201], v[20:21], v[204:205] op_sel_hi:[1,0]
	v_pk_mul_f32 v[202:203], v[22:23], v[204:205] op_sel_hi:[1,0]
	v_pk_mul_f32 v[16:17], v[20:21], v[16:17]
	v_pk_mul_f32 v[18:19], v[22:23], v[18:19]
	v_exp_f32_e32 v200, v200
	v_exp_f32_e32 v201, v201
	v_exp_f32_e32 v202, v202
	v_exp_f32_e32 v203, v203
	s_nop 0
	v_pk_add_f32 v[200:201], v[200:201], 1.0 op_sel_hi:[1,0]
	v_pk_add_f32 v[202:203], v[202:203], 1.0 op_sel_hi:[1,0]
	v_rcp_f32_e32 v200, v200
	v_rcp_f32_e32 v201, v201
	v_rcp_f32_e32 v202, v202
	v_rcp_f32_e32 v203, v203
	s_nop 0
	v_pk_mul_f32 v[16:17], v[200:201], v[16:17]
	v_pk_mul_f32 v[18:19], v[202:203], v[18:19]
	v_pk_mul_f32 v[206:207], v[28:29], v[204:205] op_sel_hi:[1,0]
	v_pk_mul_f32 v[208:209], v[30:31], v[204:205] op_sel_hi:[1,0]
	v_pk_mul_f32 v[24:25], v[28:29], v[24:25]
	v_pk_mul_f32 v[26:27], v[30:31], v[26:27]
	v_exp_f32_e32 v206, v206
	v_exp_f32_e32 v207, v207
	v_exp_f32_e32 v208, v208
	v_exp_f32_e32 v209, v209
	s_nop 0
	v_pk_add_f32 v[206:207], v[206:207], 1.0 op_sel_hi:[1,0]
	v_pk_add_f32 v[208:209], v[208:209], 1.0 op_sel_hi:[1,0]
	v_rcp_f32_e32 v206, v206
	v_rcp_f32_e32 v207, v207
	v_rcp_f32_e32 v208, v208
	v_rcp_f32_e32 v209, v209
	s_nop 0
	v_pk_mul_f32 v[24:25], v[206:207], v[24:25]
	v_pk_mul_f32 v[26:27], v[208:209], v[26:27]
	v_cvt_pk_bf16_f32 v28, v24, v25
	v_cvt_pk_bf16_f32 v29, v26, v27
	v_cvt_pk_bf16_f32 v30, v16, v17
	v_cvt_pk_bf16_f32 v31, v18, v19
	v_add_u32_e32 v20, 0xa0, v156
	v_mad_i64_i32 v[20:21], s[26:27], v20, s56, v[112:113]
	v_lshl_add_u64 v[20:21], v[20:21], 0, v[114:115]
	global_store_dwordx4 v[20:21], v[28:31], off
	v_pk_mul_f32 v[200:201], v[4:5], v[204:205] op_sel_hi:[1,0]
	v_pk_mul_f32 v[202:203], v[6:7], v[204:205] op_sel_hi:[1,0]
	v_pk_mul_f32 v[0:1], v[4:5], v[0:1]
	v_pk_mul_f32 v[2:3], v[6:7], v[2:3]
	v_exp_f32_e32 v200, v200
	v_exp_f32_e32 v201, v201
	v_exp_f32_e32 v202, v202
	v_exp_f32_e32 v203, v203
	s_nop 0
	v_pk_add_f32 v[200:201], v[200:201], 1.0 op_sel_hi:[1,0]
	v_pk_add_f32 v[202:203], v[202:203], 1.0 op_sel_hi:[1,0]
	v_rcp_f32_e32 v200, v200
	v_rcp_f32_e32 v201, v201
	v_rcp_f32_e32 v202, v202
	v_rcp_f32_e32 v203, v203
	s_nop 0
	v_pk_mul_f32 v[0:1], v[200:201], v[0:1]
	v_pk_mul_f32 v[2:3], v[202:203], v[2:3]
	v_pk_mul_f32 v[206:207], v[12:13], v[204:205] op_sel_hi:[1,0]
	v_pk_mul_f32 v[208:209], v[14:15], v[204:205] op_sel_hi:[1,0]
	v_pk_mul_f32 v[8:9], v[12:13], v[8:9]
	v_pk_mul_f32 v[10:11], v[14:15], v[10:11]
	v_exp_f32_e32 v206, v206
	v_exp_f32_e32 v207, v207
	v_exp_f32_e32 v208, v208
	v_exp_f32_e32 v209, v209
	s_nop 0
	v_pk_add_f32 v[206:207], v[206:207], 1.0 op_sel_hi:[1,0]
	v_pk_add_f32 v[208:209], v[208:209], 1.0 op_sel_hi:[1,0]
	v_rcp_f32_e32 v206, v206
	v_rcp_f32_e32 v207, v207
	v_rcp_f32_e32 v208, v208
	v_rcp_f32_e32 v209, v209
	s_nop 0
	v_pk_mul_f32 v[8:9], v[206:207], v[8:9]
	v_pk_mul_f32 v[10:11], v[208:209], v[10:11]
	v_cvt_pk_bf16_f32 v12, v8, v9
	v_cvt_pk_bf16_f32 v13, v10, v11
	v_cvt_pk_bf16_f32 v14, v0, v1
	v_cvt_pk_bf16_f32 v15, v2, v3
	v_add_u32_e32 v4, 0xb0, v156
	v_mad_i64_i32 v[4:5], s[26:27], v4, s56, v[112:113]
	v_lshl_add_u64 v[4:5], v[4:5], 0, v[114:115]
	s_andn2_b64 vcc, exec, s[4:5]
	s_mov_b64 s[4:5], -1
	global_store_dwordx4 v[4:5], v[12:15], off
	s_cbranch_vccnz .LBB0_794
	s_andn2_b64 vcc, exec, s[6:7]
	s_cbranch_vccnz .LBB0_793
	s_barrier
	s_branch .LBB0_793
